# EpiRes GEMM epilogue bf16 path rewritten: rolling residual prefetch into dead accumulator registers, row-sum atomics deferred to the end (permlane swap reduction)
# speedup vs baseline: 1.0364x; 1.0143x over previous
;     __device__ __forceinline__ void operator()(const f32x4 (&acc)[2][2][4][2], const Unit& u, int wr, int wc, int fr, int fq) const {
;         asm volatile("" : "+v"(fr), "+v"(fq));
;         const int row0 = u.pm * BM + wr * 64 + fr, col0 = u.pn * BM + wc * 32 + 8 * fq;
;         const int seq = seq_of_row(u.pm * BM);
;         const float* gp = gate + (size_t)seq * MODW + col0; const float* gsp = gs + (size_t)seq * DM + col0;
;         f32x4 gv[2][2], gsv[2][2];
; #pragma unroll
;         for (int bj = 0; bj < 2; ++bj)
; #pragma unroll
;             for (int n = 0; n < 2; ++n) { gv[bj][n] = *(const f32x4*)(gp + bj * HALF + 4 * n); gsv[bj][n] = *(const f32x4*)(gsp + bj * HALF + 4 * n); }
;         const bool f32in = (xf0 != nullptr);
;         const float* fbase = f32in ? ((u.pm * BM < 16384 ? xf0 + (size_t)row0 * DM : xf1 + (size_t)(row0 - 16384) * DM) + col0) : nullptr;
;         bf16_t* hbase = xh + (size_t)row0 * DM + col0;
;         f32x4 xr[1][2][2];
;     ...
; #pragma unroll
;         for (int g8 = 0; g8 < 8; ++g8) { const int ai = g8 >> 2, m = g8 & 3;
;             ERES_LOAD(0, g8);
;             const int r = row0 + ai * HALF + m * 16; float s = 0.f;
; #pragma unroll
;             for (int bj = 0; bj < 2; ++bj) { const f32x4 x0 = xr[0][bj][0] + gv[bj][0] * acc[ai][bj][m][0], x1 = xr[0][bj][1] + gv[bj][1] * acc[ai][bj][m][1];
;                 s += (x0[0] * x0[0] + x0[1] * x0[1]) + (x0[2] * x0[2] + x0[3] * x0[3]) + (x1[0] * x1[0] + x1[1] * x1[1]) + (x1[2] * x1[2] + x1[3] * x1[3]);
;                 u32x4 w; w.x = cvt_pk_bf16_asm(x0[0], x0[1]); w.y = cvt_pk_bf16_asm(x0[2], x0[3]); w.z = cvt_pk_bf16_asm(x1[0], x1[1]); w.w = cvt_pk_bf16_asm(x1[2], x1[3]);
;                 *(u32x4*)(xh + (size_t)r * DM + col0 + bj * HALF) = w;
;                 if (xb) { const f32x4 h0 = x0 * gsv[bj][0], h1 = x1 * gsv[bj][1]; u32x4 wb; wb.x = cvt_pk_bf16_asm(h0[0], h0[1]); wb.y = cvt_pk_bf16_asm(h0[2], h0[3]); wb.z = cvt_pk_bf16_asm(h1[0], h1[1]); wb.w = cvt_pk_bf16_asm(h1[2], h1[3]);
;                     *(u32x4*)(xb + (size_t)r * DM + col0 + bj * HALF) = wb; } }
;             s += __shfl_xor(s, 16); s += __shfl_xor(s, 32); if (fq == 0) (void)__hip_atomic_fetch_add(ssn + r, (u64)(s * SSK), __ATOMIC_RELAXED, __HIP_MEMORY_SCOPE_AGENT);
;         }
.Lres_bf16:
	v_lshlrev_b32_e32 v195, 11, v194
	v_lshl_add_u32 v195, v192, 1, v195
	v_lshlrev_b32_e32 v193, 3, v194
	s_mov_b64 s[8:9], s[28:29]
	global_load_dwordx4 v[162:165], v195, s[8:9]
	global_load_dwordx4 v[166:169], v195, s[8:9] offset:256
	s_and_b64 vcc, exec, s[52:53]
	s_waitcnt vmcnt(0)
	v_lshlrev_b32_e32 v170, 16, v162
	v_and_b32_e32 v171, 0xffff0000, v162
	v_pk_fma_f32 v[158:159], v[78:79], v[158:159], v[170:171]
	v_lshlrev_b32_e32 v172, 16, v163
	v_and_b32_e32 v173, 0xffff0000, v163
	v_pk_fma_f32 v[160:161], v[80:81], v[160:161], v[172:173]
	v_lshlrev_b32_e32 v174, 16, v164
	v_and_b32_e32 v175, 0xffff0000, v164
	v_pk_fma_f32 v[154:155], v[74:75], v[154:155], v[174:175]
	v_lshlrev_b32_e32 v176, 16, v165
	v_and_b32_e32 v177, 0xffff0000, v165
	v_pk_fma_f32 v[156:157], v[76:77], v[156:157], v[176:177]
	v_lshlrev_b32_e32 v170, 16, v166
	v_and_b32_e32 v171, 0xffff0000, v166
	v_pk_fma_f32 v[150:151], v[62:63], v[150:151], v[170:171]
	v_lshlrev_b32_e32 v172, 16, v167
	v_and_b32_e32 v173, 0xffff0000, v167
	v_pk_fma_f32 v[152:153], v[64:65], v[152:153], v[172:173]
	v_lshlrev_b32_e32 v174, 16, v168
	v_and_b32_e32 v175, 0xffff0000, v168
	v_pk_fma_f32 v[146:147], v[58:59], v[146:147], v[174:175]
	v_lshlrev_b32_e32 v176, 16, v169
	v_and_b32_e32 v177, 0xffff0000, v169
	v_pk_fma_f32 v[148:149], v[60:61], v[148:149], v[176:177]
	v_cvt_pk_bf16_f32 v170, v158, v159
	v_cvt_pk_bf16_f32 v171, v160, v161
	v_cvt_pk_bf16_f32 v172, v154, v155
	v_cvt_pk_bf16_f32 v173, v156, v157
	v_cvt_pk_bf16_f32 v174, v150, v151
	v_cvt_pk_bf16_f32 v175, v152, v153
	v_cvt_pk_bf16_f32 v176, v146, v147
	v_cvt_pk_bf16_f32 v177, v148, v149
	s_mov_b64 s[8:9], s[28:29]
	global_store_dwordx4 v195, v[170:173], s[8:9]
	global_store_dwordx4 v195, v[174:177], s[8:9] offset:256
	v_mul_f32_e32 v196, v158, v158
	v_mul_f32_e32 v162, v159, v159
	v_fmac_f32_e32 v196, v160, v160
	v_fmac_f32_e32 v162, v161, v161
	v_fmac_f32_e32 v196, v154, v154
	v_fmac_f32_e32 v162, v155, v155
	v_fmac_f32_e32 v196, v156, v156
	v_fmac_f32_e32 v162, v157, v157
	v_fmac_f32_e32 v196, v150, v150
	v_fmac_f32_e32 v162, v151, v151
	v_fmac_f32_e32 v196, v152, v152
	v_fmac_f32_e32 v162, v153, v153
	v_fmac_f32_e32 v196, v146, v146
	v_fmac_f32_e32 v162, v147, v147
	v_fmac_f32_e32 v196, v148, v148
	v_fmac_f32_e32 v162, v149, v149
	v_add_f32_e32 v196, v196, v162
	s_cbranch_vccz .Lres_noxb_0
	v_pk_mul_f32 v[158:159], v[158:159], v[70:71]
	v_pk_mul_f32 v[160:161], v[160:161], v[72:73]
	v_pk_mul_f32 v[154:155], v[154:155], v[66:67]
	v_pk_mul_f32 v[156:157], v[156:157], v[68:69]
	v_pk_mul_f32 v[150:151], v[150:151], v[54:55]
	v_pk_mul_f32 v[152:153], v[152:153], v[56:57]
	v_pk_mul_f32 v[146:147], v[146:147], v[50:51]
	v_pk_mul_f32 v[148:149], v[148:149], v[52:53]
	v_cvt_pk_bf16_f32 v162, v158, v159
	v_cvt_pk_bf16_f32 v163, v160, v161
	v_cvt_pk_bf16_f32 v164, v154, v155
	v_cvt_pk_bf16_f32 v165, v156, v157
	v_cvt_pk_bf16_f32 v166, v150, v151
	v_cvt_pk_bf16_f32 v167, v152, v153
	v_cvt_pk_bf16_f32 v168, v146, v147
	v_cvt_pk_bf16_f32 v169, v148, v149
	s_mov_b64 s[4:5], s[62:63]
	global_store_dwordx4 v195, v[162:165], s[4:5]
	global_store_dwordx4 v195, v[166:169], s[4:5] offset:256
.Lres_noxb_0:
	s_add_u32 s8, s28, 0x8000
	s_addc_u32 s9, s29, 0
	global_load_dwordx4 v[162:165], v195, s[8:9]
	global_load_dwordx4 v[166:169], v195, s[8:9] offset:256
	s_add_u32 s8, s28, 0x10000
	s_addc_u32 s9, s29, 0
	global_load_dwordx4 v[158:161], v195, s[8:9]
	global_load_dwordx4 v[154:157], v195, s[8:9] offset:256
	s_add_u32 s8, s28, 0x18000
	s_addc_u32 s9, s29, 0
	global_load_dwordx4 v[150:153], v195, s[8:9]
	global_load_dwordx4 v[146:149], v195, s[8:9] offset:256
	s_waitcnt vmcnt(4)
	v_lshlrev_b32_e32 v170, 16, v162
	v_and_b32_e32 v171, 0xffff0000, v162
	v_pk_fma_f32 v[142:143], v[78:79], v[142:143], v[170:171]
	v_lshlrev_b32_e32 v172, 16, v163
	v_and_b32_e32 v173, 0xffff0000, v163
	v_pk_fma_f32 v[144:145], v[80:81], v[144:145], v[172:173]
	v_lshlrev_b32_e32 v174, 16, v164
	v_and_b32_e32 v175, 0xffff0000, v164
	v_pk_fma_f32 v[138:139], v[74:75], v[138:139], v[174:175]
	v_lshlrev_b32_e32 v176, 16, v165
	v_and_b32_e32 v177, 0xffff0000, v165
	v_pk_fma_f32 v[140:141], v[76:77], v[140:141], v[176:177]
	v_lshlrev_b32_e32 v170, 16, v166
	v_and_b32_e32 v171, 0xffff0000, v166
	v_pk_fma_f32 v[134:135], v[62:63], v[134:135], v[170:171]
	v_lshlrev_b32_e32 v172, 16, v167
	v_and_b32_e32 v173, 0xffff0000, v167
	v_pk_fma_f32 v[136:137], v[64:65], v[136:137], v[172:173]
	v_lshlrev_b32_e32 v174, 16, v168
	v_and_b32_e32 v175, 0xffff0000, v168
	v_pk_fma_f32 v[130:131], v[58:59], v[130:131], v[174:175]
	v_lshlrev_b32_e32 v176, 16, v169
	v_and_b32_e32 v177, 0xffff0000, v169
	v_pk_fma_f32 v[132:133], v[60:61], v[132:133], v[176:177]
	v_cvt_pk_bf16_f32 v170, v142, v143
	v_cvt_pk_bf16_f32 v171, v144, v145
	v_cvt_pk_bf16_f32 v172, v138, v139
	v_cvt_pk_bf16_f32 v173, v140, v141
	v_cvt_pk_bf16_f32 v174, v134, v135
	v_cvt_pk_bf16_f32 v175, v136, v137
	v_cvt_pk_bf16_f32 v176, v130, v131
	v_cvt_pk_bf16_f32 v177, v132, v133
	s_add_u32 s8, s28, 0x8000
	s_addc_u32 s9, s29, 0
	global_store_dwordx4 v195, v[170:173], s[8:9]
	global_store_dwordx4 v195, v[174:177], s[8:9] offset:256
	v_mul_f32_e32 v197, v142, v142
	v_mul_f32_e32 v162, v143, v143
	v_fmac_f32_e32 v197, v144, v144
	v_fmac_f32_e32 v162, v145, v145
	v_fmac_f32_e32 v197, v138, v138
	v_fmac_f32_e32 v162, v139, v139
	v_fmac_f32_e32 v197, v140, v140
	v_fmac_f32_e32 v162, v141, v141
	v_fmac_f32_e32 v197, v134, v134
	v_fmac_f32_e32 v162, v135, v135
	v_fmac_f32_e32 v197, v136, v136
	v_fmac_f32_e32 v162, v137, v137
	v_fmac_f32_e32 v197, v130, v130
	v_fmac_f32_e32 v162, v131, v131
	v_fmac_f32_e32 v197, v132, v132
	v_fmac_f32_e32 v162, v133, v133
	v_add_f32_e32 v197, v197, v162
	s_cbranch_vccz .Lres_noxb_1
	v_pk_mul_f32 v[142:143], v[142:143], v[70:71]
	v_pk_mul_f32 v[144:145], v[144:145], v[72:73]
	v_pk_mul_f32 v[138:139], v[138:139], v[66:67]
	v_pk_mul_f32 v[140:141], v[140:141], v[68:69]
	v_pk_mul_f32 v[134:135], v[134:135], v[54:55]
	v_pk_mul_f32 v[136:137], v[136:137], v[56:57]
	v_pk_mul_f32 v[130:131], v[130:131], v[50:51]
	v_pk_mul_f32 v[132:133], v[132:133], v[52:53]
	v_cvt_pk_bf16_f32 v162, v142, v143
	v_cvt_pk_bf16_f32 v163, v144, v145
	v_cvt_pk_bf16_f32 v164, v138, v139
	v_cvt_pk_bf16_f32 v165, v140, v141
	v_cvt_pk_bf16_f32 v166, v134, v135
	v_cvt_pk_bf16_f32 v167, v136, v137
	v_cvt_pk_bf16_f32 v168, v130, v131
	v_cvt_pk_bf16_f32 v169, v132, v133
	s_add_u32 s4, s62, 0x8000
	s_addc_u32 s5, s63, 0
	global_store_dwordx4 v195, v[162:165], s[4:5]
	global_store_dwordx4 v195, v[166:169], s[4:5] offset:256
; __device__ __forceinline__ unsigned cvt_pk_bf16_asm(float lo, float hi) { unsigned r; asm volatile("v_cvt_pk_bf16_f32 %0, %1, %2" : "=v"(r) : "v"(lo), "v"(hi)); return r; }
;     __device__ __forceinline__ void operator()(const f32x4 (&acc)[2][2][4][2], const Unit& u, int wr, int wc, int fr, int fq) const {
;     ...
; #pragma unroll
;         for (int g8 = 0; g8 < 8; ++g8) { const int ai = g8 >> 2, m = g8 & 3;
;             ERES_LOAD(0, g8);
;             const int r = row0 + ai * HALF + m * 16; float s = 0.f;
; #pragma unroll
;             for (int bj = 0; bj < 2; ++bj) { const f32x4 x0 = xr[0][bj][0] + gv[bj][0] * acc[ai][bj][m][0], x1 = xr[0][bj][1] + gv[bj][1] * acc[ai][bj][m][1];
;                 s += (x0[0] * x0[0] + x0[1] * x0[1]) + (x0[2] * x0[2] + x0[3] * x0[3]) + (x1[0] * x1[0] + x1[1] * x1[1]) + (x1[2] * x1[2] + x1[3] * x1[3]);
;                 u32x4 w; w.x = cvt_pk_bf16_asm(x0[0], x0[1]); w.y = cvt_pk_bf16_asm(x0[2], x0[3]); w.z = cvt_pk_bf16_asm(x1[0], x1[1]); w.w = cvt_pk_bf16_asm(x1[2], x1[3]);
;                 *(u32x4*)(xh + (size_t)r * DM + col0 + bj * HALF) = w;
;                 if (xb) { const f32x4 h0 = x0 * gsv[bj][0], h1 = x1 * gsv[bj][1]; u32x4 wb; wb.x = cvt_pk_bf16_asm(h0[0], h0[1]); wb.y = cvt_pk_bf16_asm(h0[2], h0[3]); wb.z = cvt_pk_bf16_asm(h1[0], h1[1]); wb.w = cvt_pk_bf16_asm(h1[2], h1[3]);
;                     *(u32x4*)(xb + (size_t)r * DM + col0 + bj * HALF) = wb; } }
;             s += __shfl_xor(s, 16); s += __shfl_xor(s, 32); if (fq == 0) (void)__hip_atomic_fetch_add(ssn + r, (u64)(s * SSK), __ATOMIC_RELAXED, __HIP_MEMORY_SCOPE_AGENT);
;         }
.Lres_noxb_1:
	s_add_u32 s8, s28, 0x40000
	s_addc_u32 s9, s29, 0
	global_load_dwordx4 v[142:145], v195, s[8:9]
	global_load_dwordx4 v[138:141], v195, s[8:9] offset:256
	s_add_u32 s8, s28, 0x48000
	s_addc_u32 s9, s29, 0
	global_load_dwordx4 v[134:137], v195, s[8:9]
	global_load_dwordx4 v[130:133], v195, s[8:9] offset:256
	s_waitcnt vmcnt(8)
	v_lshlrev_b32_e32 v170, 16, v158
	v_and_b32_e32 v171, 0xffff0000, v158
	v_pk_fma_f32 v[126:127], v[78:79], v[126:127], v[170:171]
	v_lshlrev_b32_e32 v172, 16, v159
	v_and_b32_e32 v173, 0xffff0000, v159
	v_pk_fma_f32 v[128:129], v[80:81], v[128:129], v[172:173]
	v_lshlrev_b32_e32 v174, 16, v160
	v_and_b32_e32 v175, 0xffff0000, v160
	v_pk_fma_f32 v[122:123], v[74:75], v[122:123], v[174:175]
	v_lshlrev_b32_e32 v176, 16, v161
	v_and_b32_e32 v177, 0xffff0000, v161
	v_pk_fma_f32 v[124:125], v[76:77], v[124:125], v[176:177]
	v_lshlrev_b32_e32 v170, 16, v154
	v_and_b32_e32 v171, 0xffff0000, v154
	v_pk_fma_f32 v[118:119], v[62:63], v[118:119], v[170:171]
	v_lshlrev_b32_e32 v172, 16, v155
	v_and_b32_e32 v173, 0xffff0000, v155
	v_pk_fma_f32 v[120:121], v[64:65], v[120:121], v[172:173]
	v_lshlrev_b32_e32 v174, 16, v156
	v_and_b32_e32 v175, 0xffff0000, v156
	v_pk_fma_f32 v[114:115], v[58:59], v[114:115], v[174:175]
	v_lshlrev_b32_e32 v176, 16, v157
	v_and_b32_e32 v177, 0xffff0000, v157
	v_pk_fma_f32 v[116:117], v[60:61], v[116:117], v[176:177]
	v_cvt_pk_bf16_f32 v170, v126, v127
	v_cvt_pk_bf16_f32 v171, v128, v129
	v_cvt_pk_bf16_f32 v172, v122, v123
	v_cvt_pk_bf16_f32 v173, v124, v125
	v_cvt_pk_bf16_f32 v174, v118, v119
	v_cvt_pk_bf16_f32 v175, v120, v121
	v_cvt_pk_bf16_f32 v176, v114, v115
	v_cvt_pk_bf16_f32 v177, v116, v117
	s_add_u32 s8, s28, 0x10000
	s_addc_u32 s9, s29, 0
	global_store_dwordx4 v195, v[170:173], s[8:9]
	global_store_dwordx4 v195, v[174:177], s[8:9] offset:256
	v_mul_f32_e32 v198, v126, v126
	v_mul_f32_e32 v158, v127, v127
	v_fmac_f32_e32 v198, v128, v128
	v_fmac_f32_e32 v158, v129, v129
	v_fmac_f32_e32 v198, v122, v122
	v_fmac_f32_e32 v158, v123, v123
	v_fmac_f32_e32 v198, v124, v124
	v_fmac_f32_e32 v158, v125, v125
	v_fmac_f32_e32 v198, v118, v118
	v_fmac_f32_e32 v158, v119, v119
	v_fmac_f32_e32 v198, v120, v120
	v_fmac_f32_e32 v158, v121, v121
	v_fmac_f32_e32 v198, v114, v114
	v_fmac_f32_e32 v158, v115, v115
	v_fmac_f32_e32 v198, v116, v116
	v_fmac_f32_e32 v158, v117, v117
	v_add_f32_e32 v198, v198, v158
	s_cbranch_vccz .Lres_noxb_2
	v_pk_mul_f32 v[126:127], v[126:127], v[70:71]
	v_pk_mul_f32 v[128:129], v[128:129], v[72:73]
	v_pk_mul_f32 v[122:123], v[122:123], v[66:67]
	v_pk_mul_f32 v[124:125], v[124:125], v[68:69]
	v_pk_mul_f32 v[118:119], v[118:119], v[54:55]
	v_pk_mul_f32 v[120:121], v[120:121], v[56:57]
	v_pk_mul_f32 v[114:115], v[114:115], v[50:51]
	v_pk_mul_f32 v[116:117], v[116:117], v[52:53]
	v_cvt_pk_bf16_f32 v158, v126, v127
	v_cvt_pk_bf16_f32 v159, v128, v129
	v_cvt_pk_bf16_f32 v160, v122, v123
	v_cvt_pk_bf16_f32 v161, v124, v125
	v_cvt_pk_bf16_f32 v154, v118, v119
	v_cvt_pk_bf16_f32 v155, v120, v121
	v_cvt_pk_bf16_f32 v156, v114, v115
	v_cvt_pk_bf16_f32 v157, v116, v117
	s_add_u32 s4, s62, 0x10000
	s_addc_u32 s5, s63, 0
	global_store_dwordx4 v195, v[158:161], s[4:5]
	global_store_dwordx4 v195, v[154:157], s[4:5] offset:256
.Lres_noxb_2:
	s_add_u32 s8, s28, 0x50000
	s_addc_u32 s9, s29, 0
	global_load_dwordx4 v[126:129], v195, s[8:9]
	global_load_dwordx4 v[122:125], v195, s[8:9] offset:256
	s_add_u32 s8, s28, 0x58000
	s_addc_u32 s9, s29, 0
	global_load_dwordx4 v[118:121], v195, s[8:9]
	global_load_dwordx4 v[114:117], v195, s[8:9] offset:256
	s_waitcnt vmcnt(12)
	v_lshlrev_b32_e32 v170, 16, v150
	v_and_b32_e32 v171, 0xffff0000, v150
	v_pk_fma_f32 v[110:111], v[78:79], v[110:111], v[170:171]
	v_lshlrev_b32_e32 v172, 16, v151
	v_and_b32_e32 v173, 0xffff0000, v151
	v_pk_fma_f32 v[112:113], v[80:81], v[112:113], v[172:173]
	v_lshlrev_b32_e32 v174, 16, v152
	v_and_b32_e32 v175, 0xffff0000, v152
	v_pk_fma_f32 v[106:107], v[74:75], v[106:107], v[174:175]
	v_lshlrev_b32_e32 v176, 16, v153
	v_and_b32_e32 v177, 0xffff0000, v153
	v_pk_fma_f32 v[108:109], v[76:77], v[108:109], v[176:177]
	v_lshlrev_b32_e32 v170, 16, v146
	v_and_b32_e32 v171, 0xffff0000, v146
	v_pk_fma_f32 v[102:103], v[62:63], v[102:103], v[170:171]
	v_lshlrev_b32_e32 v172, 16, v147
	v_and_b32_e32 v173, 0xffff0000, v147
	v_pk_fma_f32 v[104:105], v[64:65], v[104:105], v[172:173]
	v_lshlrev_b32_e32 v174, 16, v148
	v_and_b32_e32 v175, 0xffff0000, v148
	v_pk_fma_f32 v[98:99], v[58:59], v[98:99], v[174:175]
	v_lshlrev_b32_e32 v176, 16, v149
	v_and_b32_e32 v177, 0xffff0000, v149
	v_pk_fma_f32 v[100:101], v[60:61], v[100:101], v[176:177]
	v_cvt_pk_bf16_f32 v170, v110, v111
	v_cvt_pk_bf16_f32 v171, v112, v113
	v_cvt_pk_bf16_f32 v172, v106, v107
	v_cvt_pk_bf16_f32 v173, v108, v109
	v_cvt_pk_bf16_f32 v174, v102, v103
	v_cvt_pk_bf16_f32 v175, v104, v105
	v_cvt_pk_bf16_f32 v176, v98, v99
	v_cvt_pk_bf16_f32 v177, v100, v101
	s_add_u32 s8, s28, 0x18000
	s_addc_u32 s9, s29, 0
	global_store_dwordx4 v195, v[170:173], s[8:9]
	global_store_dwordx4 v195, v[174:177], s[8:9] offset:256
	v_mul_f32_e32 v199, v110, v110
	v_mul_f32_e32 v150, v111, v111
	v_fmac_f32_e32 v199, v112, v112
	v_fmac_f32_e32 v150, v113, v113
	v_fmac_f32_e32 v199, v106, v106
	v_fmac_f32_e32 v150, v107, v107
	v_fmac_f32_e32 v199, v108, v108
	v_fmac_f32_e32 v150, v109, v109
	v_fmac_f32_e32 v199, v102, v102
	v_fmac_f32_e32 v150, v103, v103
	v_fmac_f32_e32 v199, v104, v104
	v_fmac_f32_e32 v150, v105, v105
	v_fmac_f32_e32 v199, v98, v98
	v_fmac_f32_e32 v150, v99, v99
	v_fmac_f32_e32 v199, v100, v100
	v_fmac_f32_e32 v150, v101, v101
	v_add_f32_e32 v199, v199, v150
	s_cbranch_vccz .Lres_noxb_3
	v_pk_mul_f32 v[110:111], v[110:111], v[70:71]
	v_pk_mul_f32 v[112:113], v[112:113], v[72:73]
	v_pk_mul_f32 v[106:107], v[106:107], v[66:67]
	v_pk_mul_f32 v[108:109], v[108:109], v[68:69]
	v_pk_mul_f32 v[102:103], v[102:103], v[54:55]
	v_pk_mul_f32 v[104:105], v[104:105], v[56:57]
	v_pk_mul_f32 v[98:99], v[98:99], v[50:51]
	v_pk_mul_f32 v[100:101], v[100:101], v[52:53]
	v_cvt_pk_bf16_f32 v150, v110, v111
	v_cvt_pk_bf16_f32 v151, v112, v113
	v_cvt_pk_bf16_f32 v152, v106, v107
	v_cvt_pk_bf16_f32 v153, v108, v109
	v_cvt_pk_bf16_f32 v146, v102, v103
	v_cvt_pk_bf16_f32 v147, v104, v105
	v_cvt_pk_bf16_f32 v148, v98, v99
	v_cvt_pk_bf16_f32 v149, v100, v101
	s_add_u32 s4, s62, 0x18000
	s_addc_u32 s5, s63, 0
	global_store_dwordx4 v195, v[150:153], s[4:5]
	global_store_dwordx4 v195, v[146:149], s[4:5] offset:256
; __device__ __forceinline__ unsigned cvt_pk_bf16_asm(float lo, float hi) { unsigned r; asm volatile("v_cvt_pk_bf16_f32 %0, %1, %2" : "=v"(r) : "v"(lo), "v"(hi)); return r; }
;     __device__ __forceinline__ void operator()(const f32x4 (&acc)[2][2][4][2], const Unit& u, int wr, int wc, int fr, int fq) const {
;     ...
; #pragma unroll
;         for (int g8 = 0; g8 < 8; ++g8) { const int ai = g8 >> 2, m = g8 & 3;
;             ERES_LOAD(0, g8);
;             const int r = row0 + ai * HALF + m * 16; float s = 0.f;
; #pragma unroll
;             for (int bj = 0; bj < 2; ++bj) { const f32x4 x0 = xr[0][bj][0] + gv[bj][0] * acc[ai][bj][m][0], x1 = xr[0][bj][1] + gv[bj][1] * acc[ai][bj][m][1];
;                 s += (x0[0] * x0[0] + x0[1] * x0[1]) + (x0[2] * x0[2] + x0[3] * x0[3]) + (x1[0] * x1[0] + x1[1] * x1[1]) + (x1[2] * x1[2] + x1[3] * x1[3]);
;                 u32x4 w; w.x = cvt_pk_bf16_asm(x0[0], x0[1]); w.y = cvt_pk_bf16_asm(x0[2], x0[3]); w.z = cvt_pk_bf16_asm(x1[0], x1[1]); w.w = cvt_pk_bf16_asm(x1[2], x1[3]);
;                 *(u32x4*)(xh + (size_t)r * DM + col0 + bj * HALF) = w;
;                 if (xb) { const f32x4 h0 = x0 * gsv[bj][0], h1 = x1 * gsv[bj][1]; u32x4 wb; wb.x = cvt_pk_bf16_asm(h0[0], h0[1]); wb.y = cvt_pk_bf16_asm(h0[2], h0[3]); wb.z = cvt_pk_bf16_asm(h1[0], h1[1]); wb.w = cvt_pk_bf16_asm(h1[2], h1[3]);
;                     *(u32x4*)(xb + (size_t)r * DM + col0 + bj * HALF) = wb; } }
;             s += __shfl_xor(s, 16); s += __shfl_xor(s, 32); if (fq == 0) (void)__hip_atomic_fetch_add(ssn + r, (u64)(s * SSK), __ATOMIC_RELAXED, __HIP_MEMORY_SCOPE_AGENT);
;         }
.Lres_noxb_3:
	s_waitcnt vmcnt(10)
	v_lshlrev_b32_e32 v170, 16, v142
	v_and_b32_e32 v171, 0xffff0000, v142
	v_pk_fma_f32 v[94:95], v[78:79], v[94:95], v[170:171]
	v_lshlrev_b32_e32 v172, 16, v143
	v_and_b32_e32 v173, 0xffff0000, v143
	v_pk_fma_f32 v[96:97], v[80:81], v[96:97], v[172:173]
	v_lshlrev_b32_e32 v174, 16, v144
	v_and_b32_e32 v175, 0xffff0000, v144
	v_pk_fma_f32 v[90:91], v[74:75], v[90:91], v[174:175]
	v_lshlrev_b32_e32 v176, 16, v145
	v_and_b32_e32 v177, 0xffff0000, v145
	v_pk_fma_f32 v[92:93], v[76:77], v[92:93], v[176:177]
	v_lshlrev_b32_e32 v170, 16, v138
	v_and_b32_e32 v171, 0xffff0000, v138
	v_pk_fma_f32 v[86:87], v[62:63], v[86:87], v[170:171]
	v_lshlrev_b32_e32 v172, 16, v139
	v_and_b32_e32 v173, 0xffff0000, v139
	v_pk_fma_f32 v[88:89], v[64:65], v[88:89], v[172:173]
	v_lshlrev_b32_e32 v174, 16, v140
	v_and_b32_e32 v175, 0xffff0000, v140
	v_pk_fma_f32 v[82:83], v[58:59], v[82:83], v[174:175]
	v_lshlrev_b32_e32 v176, 16, v141
	v_and_b32_e32 v177, 0xffff0000, v141
	v_pk_fma_f32 v[84:85], v[60:61], v[84:85], v[176:177]
	v_cvt_pk_bf16_f32 v170, v94, v95
	v_cvt_pk_bf16_f32 v171, v96, v97
	v_cvt_pk_bf16_f32 v172, v90, v91
	v_cvt_pk_bf16_f32 v173, v92, v93
	v_cvt_pk_bf16_f32 v174, v86, v87
	v_cvt_pk_bf16_f32 v175, v88, v89
	v_cvt_pk_bf16_f32 v176, v82, v83
	v_cvt_pk_bf16_f32 v177, v84, v85
	s_add_u32 s8, s28, 0x40000
	s_addc_u32 s9, s29, 0
	global_store_dwordx4 v195, v[170:173], s[8:9]
	global_store_dwordx4 v195, v[174:177], s[8:9] offset:256
	v_mul_f32_e32 v200, v94, v94
	v_mul_f32_e32 v142, v95, v95
	v_fmac_f32_e32 v200, v96, v96
	v_fmac_f32_e32 v142, v97, v97
	v_fmac_f32_e32 v200, v90, v90
	v_fmac_f32_e32 v142, v91, v91
	v_fmac_f32_e32 v200, v92, v92
	v_fmac_f32_e32 v142, v93, v93
	v_fmac_f32_e32 v200, v86, v86
	v_fmac_f32_e32 v142, v87, v87
	v_fmac_f32_e32 v200, v88, v88
	v_fmac_f32_e32 v142, v89, v89
	v_fmac_f32_e32 v200, v82, v82
	v_fmac_f32_e32 v142, v83, v83
	v_fmac_f32_e32 v200, v84, v84
	v_fmac_f32_e32 v142, v85, v85
	v_add_f32_e32 v200, v200, v142
	s_cbranch_vccz .Lres_noxb_4
	v_pk_mul_f32 v[94:95], v[94:95], v[70:71]
	v_pk_mul_f32 v[96:97], v[96:97], v[72:73]
	v_pk_mul_f32 v[90:91], v[90:91], v[66:67]
	v_pk_mul_f32 v[92:93], v[92:93], v[68:69]
	v_pk_mul_f32 v[86:87], v[86:87], v[54:55]
	v_pk_mul_f32 v[88:89], v[88:89], v[56:57]
	v_pk_mul_f32 v[82:83], v[82:83], v[50:51]
	v_pk_mul_f32 v[84:85], v[84:85], v[52:53]
	v_cvt_pk_bf16_f32 v142, v94, v95
	v_cvt_pk_bf16_f32 v143, v96, v97
	v_cvt_pk_bf16_f32 v144, v90, v91
	v_cvt_pk_bf16_f32 v145, v92, v93
	v_cvt_pk_bf16_f32 v138, v86, v87
	v_cvt_pk_bf16_f32 v139, v88, v89
	v_cvt_pk_bf16_f32 v140, v82, v83
	v_cvt_pk_bf16_f32 v141, v84, v85
	s_add_u32 s4, s62, 0x40000
	s_addc_u32 s5, s63, 0
	global_store_dwordx4 v195, v[142:145], s[4:5]
	global_store_dwordx4 v195, v[138:141], s[4:5] offset:256
.Lres_noxb_4:
	s_waitcnt vmcnt(10)
	v_lshlrev_b32_e32 v170, 16, v134
	v_and_b32_e32 v171, 0xffff0000, v134
	v_pk_fma_f32 v[46:47], v[78:79], v[46:47], v[170:171]
	v_lshlrev_b32_e32 v172, 16, v135
	v_and_b32_e32 v173, 0xffff0000, v135
	v_pk_fma_f32 v[48:49], v[80:81], v[48:49], v[172:173]
	v_lshlrev_b32_e32 v174, 16, v136
	v_and_b32_e32 v175, 0xffff0000, v136
	v_pk_fma_f32 v[42:43], v[74:75], v[42:43], v[174:175]
	v_lshlrev_b32_e32 v176, 16, v137
	v_and_b32_e32 v177, 0xffff0000, v137
	v_pk_fma_f32 v[44:45], v[76:77], v[44:45], v[176:177]
	v_lshlrev_b32_e32 v170, 16, v130
	v_and_b32_e32 v171, 0xffff0000, v130
	v_pk_fma_f32 v[38:39], v[62:63], v[38:39], v[170:171]
	v_lshlrev_b32_e32 v172, 16, v131
	v_and_b32_e32 v173, 0xffff0000, v131
	v_pk_fma_f32 v[40:41], v[64:65], v[40:41], v[172:173]
	v_lshlrev_b32_e32 v174, 16, v132
	v_and_b32_e32 v175, 0xffff0000, v132
	v_pk_fma_f32 v[34:35], v[58:59], v[34:35], v[174:175]
	v_lshlrev_b32_e32 v176, 16, v133
	v_and_b32_e32 v177, 0xffff0000, v133
	v_pk_fma_f32 v[36:37], v[60:61], v[36:37], v[176:177]
	v_cvt_pk_bf16_f32 v170, v46, v47
	v_cvt_pk_bf16_f32 v171, v48, v49
	v_cvt_pk_bf16_f32 v172, v42, v43
	v_cvt_pk_bf16_f32 v173, v44, v45
	v_cvt_pk_bf16_f32 v174, v38, v39
	v_cvt_pk_bf16_f32 v175, v40, v41
	v_cvt_pk_bf16_f32 v176, v34, v35
	v_cvt_pk_bf16_f32 v177, v36, v37
	s_add_u32 s8, s28, 0x48000
	s_addc_u32 s9, s29, 0
	global_store_dwordx4 v195, v[170:173], s[8:9]
	global_store_dwordx4 v195, v[174:177], s[8:9] offset:256
	v_mul_f32_e32 v202, v46, v46
	v_mul_f32_e32 v134, v47, v47
	v_fmac_f32_e32 v202, v48, v48
	v_fmac_f32_e32 v134, v49, v49
	v_fmac_f32_e32 v202, v42, v42
	v_fmac_f32_e32 v134, v43, v43
	v_fmac_f32_e32 v202, v44, v44
	v_fmac_f32_e32 v134, v45, v45
	v_fmac_f32_e32 v202, v38, v38
	v_fmac_f32_e32 v134, v39, v39
	v_fmac_f32_e32 v202, v40, v40
	v_fmac_f32_e32 v134, v41, v41
	v_fmac_f32_e32 v202, v34, v34
	v_fmac_f32_e32 v134, v35, v35
	v_fmac_f32_e32 v202, v36, v36
	v_fmac_f32_e32 v134, v37, v37
	v_add_f32_e32 v202, v202, v134
	s_cbranch_vccz .Lres_noxb_5
	v_pk_mul_f32 v[46:47], v[46:47], v[70:71]
	v_pk_mul_f32 v[48:49], v[48:49], v[72:73]
	v_pk_mul_f32 v[42:43], v[42:43], v[66:67]
	v_pk_mul_f32 v[44:45], v[44:45], v[68:69]
	v_pk_mul_f32 v[38:39], v[38:39], v[54:55]
	v_pk_mul_f32 v[40:41], v[40:41], v[56:57]
	v_pk_mul_f32 v[34:35], v[34:35], v[50:51]
	v_pk_mul_f32 v[36:37], v[36:37], v[52:53]
	v_cvt_pk_bf16_f32 v134, v46, v47
	v_cvt_pk_bf16_f32 v135, v48, v49
	v_cvt_pk_bf16_f32 v136, v42, v43
	v_cvt_pk_bf16_f32 v137, v44, v45
	v_cvt_pk_bf16_f32 v130, v38, v39
	v_cvt_pk_bf16_f32 v131, v40, v41
	v_cvt_pk_bf16_f32 v132, v34, v35
	v_cvt_pk_bf16_f32 v133, v36, v37
	s_add_u32 s4, s62, 0x48000
	s_addc_u32 s5, s63, 0
	global_store_dwordx4 v195, v[134:137], s[4:5]
	global_store_dwordx4 v195, v[130:133], s[4:5] offset:256
; __device__ __forceinline__ unsigned cvt_pk_bf16_asm(float lo, float hi) { unsigned r; asm volatile("v_cvt_pk_bf16_f32 %0, %1, %2" : "=v"(r) : "v"(lo), "v"(hi)); return r; }
;     __device__ __forceinline__ void operator()(const f32x4 (&acc)[2][2][4][2], const Unit& u, int wr, int wc, int fr, int fq) const {
;     ...
; #pragma unroll
;         for (int g8 = 0; g8 < 8; ++g8) { const int ai = g8 >> 2, m = g8 & 3;
;             ERES_LOAD(0, g8);
;             const int r = row0 + ai * HALF + m * 16; float s = 0.f;
; #pragma unroll
;             for (int bj = 0; bj < 2; ++bj) { const f32x4 x0 = xr[0][bj][0] + gv[bj][0] * acc[ai][bj][m][0], x1 = xr[0][bj][1] + gv[bj][1] * acc[ai][bj][m][1];
;                 s += (x0[0] * x0[0] + x0[1] * x0[1]) + (x0[2] * x0[2] + x0[3] * x0[3]) + (x1[0] * x1[0] + x1[1] * x1[1]) + (x1[2] * x1[2] + x1[3] * x1[3]);
;                 u32x4 w; w.x = cvt_pk_bf16_asm(x0[0], x0[1]); w.y = cvt_pk_bf16_asm(x0[2], x0[3]); w.z = cvt_pk_bf16_asm(x1[0], x1[1]); w.w = cvt_pk_bf16_asm(x1[2], x1[3]);
;                 *(u32x4*)(xh + (size_t)r * DM + col0 + bj * HALF) = w;
;                 if (xb) { const f32x4 h0 = x0 * gsv[bj][0], h1 = x1 * gsv[bj][1]; u32x4 wb; wb.x = cvt_pk_bf16_asm(h0[0], h0[1]); wb.y = cvt_pk_bf16_asm(h0[2], h0[3]); wb.z = cvt_pk_bf16_asm(h1[0], h1[1]); wb.w = cvt_pk_bf16_asm(h1[2], h1[3]);
;                     *(u32x4*)(xb + (size_t)r * DM + col0 + bj * HALF) = wb; } }
;             s += __shfl_xor(s, 16); s += __shfl_xor(s, 32); if (fq == 0) (void)__hip_atomic_fetch_add(ssn + r, (u64)(s * SSK), __ATOMIC_RELAXED, __HIP_MEMORY_SCOPE_AGENT);
;         }
.Lres_noxb_5:
	s_waitcnt vmcnt(8)
	v_lshlrev_b32_e32 v170, 16, v126
	v_and_b32_e32 v171, 0xffff0000, v126
	v_pk_fma_f32 v[30:31], v[78:79], v[30:31], v[170:171]
	v_lshlrev_b32_e32 v172, 16, v127
	v_and_b32_e32 v173, 0xffff0000, v127
	v_pk_fma_f32 v[32:33], v[80:81], v[32:33], v[172:173]
	v_lshlrev_b32_e32 v174, 16, v128
	v_and_b32_e32 v175, 0xffff0000, v128
	v_pk_fma_f32 v[26:27], v[74:75], v[26:27], v[174:175]
	v_lshlrev_b32_e32 v176, 16, v129
	v_and_b32_e32 v177, 0xffff0000, v129
	v_pk_fma_f32 v[28:29], v[76:77], v[28:29], v[176:177]
	v_lshlrev_b32_e32 v170, 16, v122
	v_and_b32_e32 v171, 0xffff0000, v122
	v_pk_fma_f32 v[22:23], v[62:63], v[22:23], v[170:171]
	v_lshlrev_b32_e32 v172, 16, v123
	v_and_b32_e32 v173, 0xffff0000, v123
	v_pk_fma_f32 v[24:25], v[64:65], v[24:25], v[172:173]
	v_lshlrev_b32_e32 v174, 16, v124
	v_and_b32_e32 v175, 0xffff0000, v124
	v_pk_fma_f32 v[18:19], v[58:59], v[18:19], v[174:175]
	v_lshlrev_b32_e32 v176, 16, v125
	v_and_b32_e32 v177, 0xffff0000, v125
	v_pk_fma_f32 v[20:21], v[60:61], v[20:21], v[176:177]
	v_cvt_pk_bf16_f32 v170, v30, v31
	v_cvt_pk_bf16_f32 v171, v32, v33
	v_cvt_pk_bf16_f32 v172, v26, v27
	v_cvt_pk_bf16_f32 v173, v28, v29
	v_cvt_pk_bf16_f32 v174, v22, v23
	v_cvt_pk_bf16_f32 v175, v24, v25
	v_cvt_pk_bf16_f32 v176, v18, v19
	v_cvt_pk_bf16_f32 v177, v20, v21
	s_add_u32 s8, s28, 0x50000
	s_addc_u32 s9, s29, 0
	global_store_dwordx4 v195, v[170:173], s[8:9]
	global_store_dwordx4 v195, v[174:177], s[8:9] offset:256
	v_mul_f32_e32 v203, v30, v30
	v_mul_f32_e32 v126, v31, v31
	v_fmac_f32_e32 v203, v32, v32
	v_fmac_f32_e32 v126, v33, v33
	v_fmac_f32_e32 v203, v26, v26
	v_fmac_f32_e32 v126, v27, v27
	v_fmac_f32_e32 v203, v28, v28
	v_fmac_f32_e32 v126, v29, v29
	v_fmac_f32_e32 v203, v22, v22
	v_fmac_f32_e32 v126, v23, v23
	v_fmac_f32_e32 v203, v24, v24
	v_fmac_f32_e32 v126, v25, v25
	v_fmac_f32_e32 v203, v18, v18
	v_fmac_f32_e32 v126, v19, v19
	v_fmac_f32_e32 v203, v20, v20
	v_fmac_f32_e32 v126, v21, v21
	v_add_f32_e32 v203, v203, v126
	s_cbranch_vccz .Lres_noxb_6
	v_pk_mul_f32 v[30:31], v[30:31], v[70:71]
	v_pk_mul_f32 v[32:33], v[32:33], v[72:73]
	v_pk_mul_f32 v[26:27], v[26:27], v[66:67]
	v_pk_mul_f32 v[28:29], v[28:29], v[68:69]
	v_pk_mul_f32 v[22:23], v[22:23], v[54:55]
	v_pk_mul_f32 v[24:25], v[24:25], v[56:57]
	v_pk_mul_f32 v[18:19], v[18:19], v[50:51]
	v_pk_mul_f32 v[20:21], v[20:21], v[52:53]
	v_cvt_pk_bf16_f32 v126, v30, v31
	v_cvt_pk_bf16_f32 v127, v32, v33
	v_cvt_pk_bf16_f32 v128, v26, v27
	v_cvt_pk_bf16_f32 v129, v28, v29
	v_cvt_pk_bf16_f32 v122, v22, v23
	v_cvt_pk_bf16_f32 v123, v24, v25
	v_cvt_pk_bf16_f32 v124, v18, v19
	v_cvt_pk_bf16_f32 v125, v20, v21
	s_add_u32 s4, s62, 0x50000
	s_addc_u32 s5, s63, 0
	global_store_dwordx4 v195, v[126:129], s[4:5]
	global_store_dwordx4 v195, v[122:125], s[4:5] offset:256
.Lres_noxb_6:
	s_waitcnt vmcnt(8)
	v_lshlrev_b32_e32 v170, 16, v118
	v_and_b32_e32 v171, 0xffff0000, v118
	v_pk_fma_f32 v[14:15], v[78:79], v[14:15], v[170:171]
	v_lshlrev_b32_e32 v172, 16, v119
	v_and_b32_e32 v173, 0xffff0000, v119
	v_pk_fma_f32 v[16:17], v[80:81], v[16:17], v[172:173]
	v_lshlrev_b32_e32 v174, 16, v120
	v_and_b32_e32 v175, 0xffff0000, v120
	v_pk_fma_f32 v[10:11], v[74:75], v[10:11], v[174:175]
	v_lshlrev_b32_e32 v176, 16, v121
	v_and_b32_e32 v177, 0xffff0000, v121
	v_pk_fma_f32 v[12:13], v[76:77], v[12:13], v[176:177]
	v_lshlrev_b32_e32 v170, 16, v114
	v_and_b32_e32 v171, 0xffff0000, v114
	v_pk_fma_f32 v[6:7], v[62:63], v[6:7], v[170:171]
	v_lshlrev_b32_e32 v172, 16, v115
	v_and_b32_e32 v173, 0xffff0000, v115
	v_pk_fma_f32 v[8:9], v[64:65], v[8:9], v[172:173]
	v_lshlrev_b32_e32 v174, 16, v116
	v_and_b32_e32 v175, 0xffff0000, v116
	v_pk_fma_f32 v[2:3], v[58:59], v[2:3], v[174:175]
	v_lshlrev_b32_e32 v176, 16, v117
	v_and_b32_e32 v177, 0xffff0000, v117
	v_pk_fma_f32 v[4:5], v[60:61], v[4:5], v[176:177]
	v_cvt_pk_bf16_f32 v170, v14, v15
	v_cvt_pk_bf16_f32 v171, v16, v17
	v_cvt_pk_bf16_f32 v172, v10, v11
	v_cvt_pk_bf16_f32 v173, v12, v13
	v_cvt_pk_bf16_f32 v174, v6, v7
	v_cvt_pk_bf16_f32 v175, v8, v9
	v_cvt_pk_bf16_f32 v176, v2, v3
	v_cvt_pk_bf16_f32 v177, v4, v5
	s_add_u32 s8, s28, 0x58000
	s_addc_u32 s9, s29, 0
	global_store_dwordx4 v195, v[170:173], s[8:9]
	global_store_dwordx4 v195, v[174:177], s[8:9] offset:256
	v_mul_f32_e32 v204, v14, v14
	v_mul_f32_e32 v118, v15, v15
	v_fmac_f32_e32 v204, v16, v16
	v_fmac_f32_e32 v118, v17, v17
	v_fmac_f32_e32 v204, v10, v10
	v_fmac_f32_e32 v118, v11, v11
	v_fmac_f32_e32 v204, v12, v12
	v_fmac_f32_e32 v118, v13, v13
	v_fmac_f32_e32 v204, v6, v6
	v_fmac_f32_e32 v118, v7, v7
	v_fmac_f32_e32 v204, v8, v8
	v_fmac_f32_e32 v118, v9, v9
	v_fmac_f32_e32 v204, v2, v2
	v_fmac_f32_e32 v118, v3, v3
	v_fmac_f32_e32 v204, v4, v4
	v_fmac_f32_e32 v118, v5, v5
	v_add_f32_e32 v204, v204, v118
	s_cbranch_vccz .Lres_noxb_7
	v_pk_mul_f32 v[14:15], v[14:15], v[70:71]
	v_pk_mul_f32 v[16:17], v[16:17], v[72:73]
	v_pk_mul_f32 v[10:11], v[10:11], v[66:67]
	v_pk_mul_f32 v[12:13], v[12:13], v[68:69]
	v_pk_mul_f32 v[6:7], v[6:7], v[54:55]
	v_pk_mul_f32 v[8:9], v[8:9], v[56:57]
	v_pk_mul_f32 v[2:3], v[2:3], v[50:51]
	v_pk_mul_f32 v[4:5], v[4:5], v[52:53]
	v_cvt_pk_bf16_f32 v118, v14, v15
	v_cvt_pk_bf16_f32 v119, v16, v17
	v_cvt_pk_bf16_f32 v120, v10, v11
	v_cvt_pk_bf16_f32 v121, v12, v13
	v_cvt_pk_bf16_f32 v114, v6, v7
	v_cvt_pk_bf16_f32 v115, v8, v9
	v_cvt_pk_bf16_f32 v116, v2, v3
	v_cvt_pk_bf16_f32 v117, v4, v5
	s_add_u32 s4, s62, 0x58000
	s_addc_u32 s5, s63, 0
	global_store_dwordx4 v195, v[118:121], s[4:5]
	global_store_dwordx4 v195, v[114:117], s[4:5] offset:256
; __device__ __forceinline__ unsigned cvt_pk_bf16_asm(float lo, float hi) { unsigned r; asm volatile("v_cvt_pk_bf16_f32 %0, %1, %2" : "=v"(r) : "v"(lo), "v"(hi)); return r; }
;     __device__ __forceinline__ void operator()(const f32x4 (&acc)[2][2][4][2], const Unit& u, int wr, int wc, int fr, int fq) const {
;     ...
;                 s += (x0[0] * x0[0] + x0[1] * x0[1]) + (x0[2] * x0[2] + x0[3] * x0[3]) + (x1[0] * x1[0] + x1[1] * x1[1]) + (x1[2] * x1[2] + x1[3] * x1[3]);
;                 u32x4 w; w.x = cvt_pk_bf16_asm(x0[0], x0[1]); w.y = cvt_pk_bf16_asm(x0[2], x0[3]); w.z = cvt_pk_bf16_asm(x1[0], x1[1]); w.w = cvt_pk_bf16_asm(x1[2], x1[3]);
;                 *(u32x4*)(xh + (size_t)r * DM + col0 + bj * HALF) = w;
;                 if (xb) { const f32x4 h0 = x0 * gsv[bj][0], h1 = x1 * gsv[bj][1]; u32x4 wb; wb.x = cvt_pk_bf16_asm(h0[0], h0[1]); wb.y = cvt_pk_bf16_asm(h0[2], h0[3]); wb.z = cvt_pk_bf16_asm(h1[0], h1[1]); wb.w = cvt_pk_bf16_asm(h1[2], h1[3]);
;                     *(u32x4*)(xb + (size_t)r * DM + col0 + bj * HALF) = wb; } }
;             s += __shfl_xor(s, 16); s += __shfl_xor(s, 32); if (fq == 0) (void)__hip_atomic_fetch_add(ssn + r, (u64)(s * SSK), __ATOMIC_RELAXED, __HIP_MEMORY_SCOPE_AGENT);
.Lres_noxb_7:
	v_mov_b32_e32 v2, v196
	v_mov_b32_e32 v6, v197
	v_mov_b32_e32 v10, v198
	v_mov_b32_e32 v14, v199
	v_mov_b32_e32 v18, v200
	v_mov_b32_e32 v22, v202
	v_mov_b32_e32 v26, v203
	v_mov_b32_e32 v34, v204
	s_nop 1
	v_permlane32_swap_b32_e32 v196, v2
	v_permlane32_swap_b32_e32 v197, v6
	v_permlane32_swap_b32_e32 v198, v10
	v_permlane32_swap_b32_e32 v199, v14
	v_permlane32_swap_b32_e32 v200, v18
	v_permlane32_swap_b32_e32 v202, v22
	v_permlane32_swap_b32_e32 v203, v26
	v_permlane32_swap_b32_e32 v204, v34
	v_add_f32_e32 v196, v196, v2
	v_add_f32_e32 v197, v197, v6
	v_add_f32_e32 v198, v198, v10
	v_add_f32_e32 v199, v199, v14
	v_add_f32_e32 v200, v200, v18
	v_add_f32_e32 v202, v202, v22
	v_add_f32_e32 v203, v203, v26
	v_add_f32_e32 v204, v204, v34
	v_mov_b32_e32 v2, v196
	v_mov_b32_e32 v6, v197
	v_mov_b32_e32 v10, v198
	v_mov_b32_e32 v14, v199
	v_mov_b32_e32 v18, v200
	v_mov_b32_e32 v22, v202
	v_mov_b32_e32 v26, v203
	v_mov_b32_e32 v34, v204
	s_nop 1
	v_permlane16_swap_b32_e32 v196, v2
	v_permlane16_swap_b32_e32 v197, v6
	v_permlane16_swap_b32_e32 v198, v10
	v_permlane16_swap_b32_e32 v199, v14
	v_permlane16_swap_b32_e32 v200, v18
	v_permlane16_swap_b32_e32 v202, v22
	v_permlane16_swap_b32_e32 v203, v26
	v_permlane16_swap_b32_e32 v204, v34
	v_add_f32_e32 v196, v196, v2
	v_add_f32_e32 v197, v197, v6
	v_add_f32_e32 v198, v198, v10
	v_add_f32_e32 v199, v199, v14
	v_add_f32_e32 v200, v200, v18
	v_add_f32_e32 v202, v202, v22
	v_add_f32_e32 v203, v203, v26
	v_add_f32_e32 v204, v204, v34
	s_mov_b64 exec, 0xffff
	v_mul_f32_e32 v38, 0x49800000, v196
	v_trunc_f32_e32 v38, v38
	v_mul_f32_e32 v39, 0x2f800000, v38
	v_floor_f32_e32 v39, v39
	v_fmac_f32_e32 v38, 0xcf800000, v39
	v_cvt_u32_f32_e32 v38, v38
	v_cvt_u32_f32_e32 v39, v39
	v_mul_f32_e32 v42, 0x49800000, v197
	v_trunc_f32_e32 v42, v42
	v_mul_f32_e32 v43, 0x2f800000, v42
	v_floor_f32_e32 v43, v43
	v_fmac_f32_e32 v42, 0xcf800000, v43
	v_cvt_u32_f32_e32 v42, v42
	v_cvt_u32_f32_e32 v43, v43
	v_mul_f32_e32 v46, 0x49800000, v198
	v_trunc_f32_e32 v46, v46
	v_mul_f32_e32 v47, 0x2f800000, v46
	v_floor_f32_e32 v47, v47
	v_fmac_f32_e32 v46, 0xcf800000, v47
	v_cvt_u32_f32_e32 v46, v46
	v_cvt_u32_f32_e32 v47, v47
	v_mul_f32_e32 v82, 0x49800000, v199
	v_trunc_f32_e32 v82, v82
	v_mul_f32_e32 v83, 0x2f800000, v82
	v_floor_f32_e32 v83, v83
	v_fmac_f32_e32 v82, 0xcf800000, v83
	v_cvt_u32_f32_e32 v82, v82
	v_cvt_u32_f32_e32 v83, v83
	v_mul_f32_e32 v86, 0x49800000, v200
	v_trunc_f32_e32 v86, v86
	v_mul_f32_e32 v87, 0x2f800000, v86
	v_floor_f32_e32 v87, v87
	v_fmac_f32_e32 v86, 0xcf800000, v87
	v_cvt_u32_f32_e32 v86, v86
	v_cvt_u32_f32_e32 v87, v87
	v_mul_f32_e32 v90, 0x49800000, v202
	v_trunc_f32_e32 v90, v90
	v_mul_f32_e32 v91, 0x2f800000, v90
	v_floor_f32_e32 v91, v91
	v_fmac_f32_e32 v90, 0xcf800000, v91
	v_cvt_u32_f32_e32 v90, v90
	v_cvt_u32_f32_e32 v91, v91
	v_mul_f32_e32 v94, 0x49800000, v203
	v_trunc_f32_e32 v94, v94
	v_mul_f32_e32 v95, 0x2f800000, v94
	v_floor_f32_e32 v95, v95
	v_fmac_f32_e32 v94, 0xcf800000, v95
	v_cvt_u32_f32_e32 v94, v94
	v_cvt_u32_f32_e32 v95, v95
	v_mul_f32_e32 v98, 0x49800000, v204
	v_trunc_f32_e32 v98, v98
	v_mul_f32_e32 v99, 0x2f800000, v98
	v_floor_f32_e32 v99, v99
	v_fmac_f32_e32 v98, 0xcf800000, v99
	v_cvt_u32_f32_e32 v98, v98
	v_cvt_u32_f32_e32 v99, v99
	global_atomic_add_x2 v193, v[38:39], s[88:89]
	global_atomic_add_x2 v193, v[42:43], s[88:89] offset:128
	global_atomic_add_x2 v193, v[46:47], s[88:89] offset:256
	global_atomic_add_x2 v193, v[82:83], s[88:89] offset:384
	global_atomic_add_x2 v193, v[86:87], s[88:89] offset:1024
	global_atomic_add_x2 v193, v[90:91], s[88:89] offset:1152
	global_atomic_add_x2 v193, v[94:95], s[88:89] offset:1280
	global_atomic_add_x2 v193, v[98:99], s[88:89] offset:1408
	s_mov_b64 exec, -1
	s_branch .LBB0_649
